# one static s_setprio 1 for waves 0-3 during the attention phase
# baseline (speedup 1.0000x reference)
; __global__ void __launch_bounds__(NWAVES * 64, 2) fwd_megakernel(Args args) {
;     ...
;         if (NGW == 2048) {
;             const int c0 = 65 * (bx & 7), wx = (bx >> 3) * NWAVES + wave;
; #pragma unroll 1
;             for (int k = 0; k < 3; ++k) { const int j = wx + 256 * k; if (j < 520) attn_item<false>(U, sink_win, c0 + (j >> 3), j & 7, wl, tbl, lane); }
;             if (wx >= 8) { const int w2 = wx - 8;
; #pragma unroll 1
;                 for (int k = 0; k < 3; ++k) { const int j = w2 + 248 * k; if (k < 2 || w2 < 24) attn_item<true>(U, sink_win, c0 + (j >> 3), j & 7, wl, tbl, lane); } }
.LBB0_597:
	s_andn2_b64 vcc, exec, s[0:1]
	s_cbranch_vccnz .LBB0_662
	s_cmp_gt_u32 s25, 3
	s_cbranch_scc1 .Lprio_p2
	s_setprio 1
